# half-height GEMM units: the never-multiplied lower A half is no longer staged into LDS (4 LDS-DMA loads per two K-tiles removed, vmcnt recounted 8 to 6)
# speedup vs baseline: 1.0111x; 1.0111x over previous
; #define PG8_STAGE(bufoff, gbase, voff) do { _Pragma("unroll") for (int _i = 0; _i < 2; ++_i) \
;         __builtin_amdgcn_global_load_lds((const unsigned*)((const char*)(gbase) + (voff)[_i]), (PG8_LAS unsigned*)(lds + (bufoff) + ldsw + _i * 8192), 16, 0, 0); } while (0)
; #define PG8_LDA(dst, b, h) do { _Pragma("unroll") for (int m = 0; m < 4; ++m) _Pragma("unroll") for (int k = 0; k < 2; ++k) dst[m][k] = *(const PG8_LAS bf16x8*)(lds + PG8_SA(b, h) + aoff + m * 2048 + k * 1024); } while (0)
; #define PG8_LDB(dst, b, h) do { _Pragma("unroll") for (int n = 0; n < 2; ++n) _Pragma("unroll") for (int k = 0; k < 2; ++k) dst[n][k] = *(const PG8_LAS bf16x8*)(lds + PG8_SB(b, h) + boff + n * 2048 + k * 1024); } while (0)
; #define PG8_WAIT_V(n) asm volatile("s_waitcnt vmcnt(" #n ")" ::: "memory")
; #define PG8_WAIT_L(n) asm volatile("s_waitcnt lgkmcnt(" #n ")" ::: "memory")
; #define PG8_BAR __builtin_amdgcn_s_barrier()
; #define PG8_SCHED __builtin_amdgcn_sched_barrier(0)
; template <class Epi, class Sched, bool ALIGN_EPI = false, bool SP2 = false, bool HALFM = false>
; __device__ __forceinline__ void gemm_phase(PG8_LAS unsigned char* lds, const Gemm g, const Sched& S, const Epi& E, const int tid_in) {
;     ...
;         for (int t = 0; t < nt; t += 2) {
;             if constexpr (Epi::KHOOK) { if (t == 8 || t == 16) E.khook(acc, cur, t, wr, wc, fr, fq); }
;             const bool last = (t == nt - 2);
;             const char* a1 = cA + (size_t)(t + 1) * kstep;
;             const char* a2 = last ? nA : cA + (size_t)(t + 2) * kstep; const char* b2 = last ? nB : cB + (size_t)(t + 2) * kstep;
;             const char* a3 = a2 + kstep; const char* b3 = b2 + kstep;
;             if (last && has_next) S.a_ready(nxt);
;             if constexpr (SP2) {
;             PG8_LDB(B0, 0, 0); PG8_LDB(B1, 0, 1); PG8_SCHED; PG8_LDA(At, 0, 0); PG8_STAGE(PG8_SA(1, 1), a1 + hstep, voffA);
;             PG8_WAIT_V(8); PG8_WAIT_L(0); PG8_BAR; PG8_MMA(0, 0, At, B0); PG8_MMA(0, 1, At, B1); PG8_BAR; PG8_SCHED;
;             PG8_LDA(At, 0, 1); PG8_STAGE(PG8_SB(0, 0), b2, voffB); PG8_STAGE(PG8_SB(0, 1), b2 + hstep, voffB); PG8_STAGE(PG8_SA(0, 0), a2, voffA);
;             PG8_WAIT_V(8); PG8_WAIT_L(0); PG8_BAR; if constexpr (!HALFM) { PG8_MMA(1, 0, At, B0); PG8_MMA(1, 1, At, B1); } PG8_BAR; PG8_SCHED;
.LBB0_71:
	s_add_u32 s0, s16, s18
	s_addc_u32 s1, s17, s19
	s_add_u32 s0, s0, 0x100
	s_addc_u32 s1, s1, 0
	s_add_u32 s12, s44, s18
	s_addc_u32 s13, s45, s19
	s_add_i32 s24, 0, 0x10000
	s_cmpk_eq_i32 s18, 0xb00
	s_cselect_b32 s23, s7, s1
	s_cselect_b32 s22, s6, s0
	v_add_u32_e32 v105, s24, v102
	s_cselect_b32 s21, s15, s13
	s_cselect_b32 s20, s14, s12
	s_add_i32 s12, 0, 0x14000
	ds_read_b128 v[96:99], v105
	ds_read_b128 v[106:109], v105 offset:1024
	ds_read_b128 v[110:113], v105 offset:2048
	ds_read_b128 v[114:117], v105 offset:3072
	v_add_u32_e32 v105, s12, v102
	ds_read_b128 v[118:121], v105
	ds_read_b128 v[122:125], v105 offset:1024
	ds_read_b128 v[126:129], v105 offset:2048
	ds_read_b128 v[130:133], v105 offset:3072
	v_lshl_add_u64 v[166:167], v[92:93], 0, s[18:19]
	s_add_i32 m0, s35, 0xc000
	ds_read_b128 v[134:137], v104
	ds_read_b128 v[138:141], v104 offset:1024
	ds_read_b128 v[142:145], v104 offset:2048
	ds_read_b128 v[146:149], v104 offset:3072
	ds_read_b128 v[150:153], v104 offset:4096
	ds_read_b128 v[154:157], v104 offset:5120
	ds_read_b128 v[158:161], v104 offset:6144
	ds_read_b128 v[162:165], v104 offset:7168
	v_lshl_add_u64 v[166:167], v[94:95], 0, s[18:19]
	s_add_i32 m0, s35, 0xe000
	s_nop 0
	s_waitcnt vmcnt(8)
	s_waitcnt lgkmcnt(0)
	s_barrier
	s_setprio 1
	s_waitcnt lgkmcnt(0)
	v_mfma_f32_16x16x32_bf16 v[62:65], v[96:99], v[134:137], v[62:65]
	v_mfma_f32_16x16x32_bf16 v[58:61], v[110:113], v[134:137], v[58:61]
	v_mfma_f32_16x16x32_bf16 v[46:49], v[96:99], v[142:145], v[46:49]
	v_mfma_f32_16x16x32_bf16 v[42:45], v[110:113], v[142:145], v[42:45]
	v_mfma_f32_16x16x32_bf16 v[30:33], v[96:99], v[150:153], v[30:33]
	v_mfma_f32_16x16x32_bf16 v[26:29], v[110:113], v[150:153], v[26:29]
	v_mfma_f32_16x16x32_bf16 v[14:17], v[96:99], v[158:161], v[14:17]
	v_mfma_f32_16x16x32_bf16 v[10:13], v[110:113], v[158:161], v[10:13]
	v_mfma_f32_16x16x32_bf16 v[62:65], v[106:109], v[138:141], v[62:65]
	v_mfma_f32_16x16x32_bf16 v[58:61], v[114:117], v[138:141], v[58:61]
	v_mfma_f32_16x16x32_bf16 v[46:49], v[106:109], v[146:149], v[46:49]
	v_mfma_f32_16x16x32_bf16 v[42:45], v[114:117], v[146:149], v[42:45]
	v_mfma_f32_16x16x32_bf16 v[30:33], v[106:109], v[154:157], v[30:33]
	v_mfma_f32_16x16x32_bf16 v[26:29], v[114:117], v[154:157], v[26:29]
	v_mfma_f32_16x16x32_bf16 v[14:17], v[106:109], v[162:165], v[14:17]
	v_mfma_f32_16x16x32_bf16 v[10:13], v[114:117], v[162:165], v[10:13]
	s_setprio 0
	s_setprio 1
	v_mfma_f32_16x16x32_bf16 v[54:57], v[118:121], v[134:137], v[54:57]
	v_mfma_f32_16x16x32_bf16 v[50:53], v[126:129], v[134:137], v[50:53]
	v_mfma_f32_16x16x32_bf16 v[38:41], v[118:121], v[142:145], v[38:41]
	v_mfma_f32_16x16x32_bf16 v[34:37], v[126:129], v[142:145], v[34:37]
	v_mfma_f32_16x16x32_bf16 v[22:25], v[118:121], v[150:153], v[22:25]
	v_mfma_f32_16x16x32_bf16 v[18:21], v[126:129], v[150:153], v[18:21]
	v_mfma_f32_16x16x32_bf16 v[6:9], v[118:121], v[158:161], v[6:9]
	v_mfma_f32_16x16x32_bf16 v[2:5], v[126:129], v[158:161], v[2:5]
	v_mfma_f32_16x16x32_bf16 v[54:57], v[122:125], v[138:141], v[54:57]
	v_mfma_f32_16x16x32_bf16 v[50:53], v[130:133], v[138:141], v[50:53]
	v_mfma_f32_16x16x32_bf16 v[38:41], v[122:125], v[146:149], v[38:41]
	v_mfma_f32_16x16x32_bf16 v[34:37], v[130:133], v[146:149], v[34:37]
	v_mfma_f32_16x16x32_bf16 v[22:25], v[122:125], v[154:157], v[22:25]
	v_mfma_f32_16x16x32_bf16 v[18:21], v[130:133], v[154:157], v[18:21]
	v_mfma_f32_16x16x32_bf16 v[6:9], v[122:125], v[162:165], v[6:9]
	v_mfma_f32_16x16x32_bf16 v[2:5], v[130:133], v[162:165], v[2:5]
	s_setprio 0
	s_barrier
	s_add_i32 s0, s24, s34
	v_lshl_add_u64 v[166:167], s[20:21], 0, v[0:1]
	s_mov_b32 m0, s0
	v_lshl_add_u64 v[168:169], s[20:21], 0, v[66:67]
	global_load_lds_dwordx4 v[166:167], off
	s_add_i32 m0, s0, 0x2000
	s_add_u32 s0, s20, 0x60000
	s_addc_u32 s1, s21, 0
	s_add_i32 s12, s12, s34
	global_load_lds_dwordx4 v[168:169], off
	v_lshl_add_u64 v[96:97], s[0:1], 0, v[0:1]
	s_mov_b32 m0, s12
	v_lshl_add_u64 v[170:171], s[22:23], 0, v[0:1]
	global_load_lds_dwordx4 v[96:97], off
	v_lshl_add_u64 v[96:97], s[0:1], 0, v[66:67]
	s_add_i32 m0, s12, 0x2000
	v_lshl_add_u64 v[172:173], s[22:23], 0, v[66:67]
	global_load_lds_dwordx4 v[96:97], off
	s_mov_b32 m0, s35
	s_nop 0
	global_load_lds_dwordx4 v[170:171], off
	s_mov_b32 m0, s36
	s_nop 0
	global_load_lds_dwordx4 v[172:173], off
	s_waitcnt vmcnt(6)
	s_waitcnt lgkmcnt(0)
	s_barrier
; #define PG8_STAGE(bufoff, gbase, voff) do { _Pragma("unroll") for (int _i = 0; _i < 2; ++_i) \
;         __builtin_amdgcn_global_load_lds((const unsigned*)((const char*)(gbase) + (voff)[_i]), (PG8_LAS unsigned*)(lds + (bufoff) + ldsw + _i * 8192), 16, 0, 0); } while (0)
; #define PG8_LDA(dst, b, h) do { _Pragma("unroll") for (int m = 0; m < 4; ++m) _Pragma("unroll") for (int k = 0; k < 2; ++k) dst[m][k] = *(const PG8_LAS bf16x8*)(lds + PG8_SA(b, h) + aoff + m * 2048 + k * 1024); } while (0)
; #define PG8_LDB(dst, b, h) do { _Pragma("unroll") for (int n = 0; n < 2; ++n) _Pragma("unroll") for (int k = 0; k < 2; ++k) dst[n][k] = *(const PG8_LAS bf16x8*)(lds + PG8_SB(b, h) + boff + n * 2048 + k * 1024); } while (0)
; #define PG8_MMA(ai, bj, At, Bt) do { __builtin_amdgcn_s_setprio(1); _Pragma("unroll") for (int m = 0; m < 4; ++m) _Pragma("unroll") for (int n = 0; n < 2; ++n) _Pragma("unroll") for (int k = 0; k < 2; ++k) \
;         acc[ai][bj][m][n] = __builtin_amdgcn_mfma_f32_16x16x32_bf16(Bt[n][k], At[m][k], acc[ai][bj][m][n], 0, 0, 0); __builtin_amdgcn_s_setprio(0); } while (0)
; #define PG8_WAIT_V(n) asm volatile("s_waitcnt vmcnt(" #n ")" ::: "memory")
; #define PG8_WAIT_L(n) asm volatile("s_waitcnt lgkmcnt(" #n ")" ::: "memory")
; #define PG8_BAR __builtin_amdgcn_s_barrier()
; #define PG8_SCHED __builtin_amdgcn_sched_barrier(0)
; template <class Epi, class Sched, bool ALIGN_EPI = false, bool SP2 = false, bool HALFM = false>
; __device__ __forceinline__ void gemm_phase(PG8_LAS unsigned char* lds, const Gemm g, const Sched& S, const Epi& E, const int tid_in) {
;     ...
;             PG8_LDB(B0, 1, 0); PG8_LDB(B1, 1, 1); PG8_SCHED; PG8_LDA(At, 1, 0); PG8_STAGE(PG8_SA(0, 1), a2 + hstep, voffA);
;             PG8_WAIT_V(8); PG8_WAIT_L(0); PG8_BAR; PG8_MMA(0, 0, At, B0); PG8_MMA(0, 1, At, B1); PG8_BAR; PG8_SCHED;
;             PG8_LDA(At, 1, 1); PG8_STAGE(PG8_SB(1, 0), b3, voffB); PG8_STAGE(PG8_SB(1, 1), b3 + hstep, voffB); PG8_STAGE(PG8_SA(1, 0), a3, voffA);
;             PG8_WAIT_V(8); PG8_WAIT_L(0); PG8_BAR; if constexpr (!HALFM) { PG8_MMA(1, 0, At, B0); PG8_MMA(1, 1, At, B1); } PG8_BAR; PG8_SCHED;
	s_barrier
	s_add_i32 s12, 0, 0x18000
	v_add_u32_e32 v105, s12, v102
	s_add_i32 s13, 0, 0x1c000
	ds_read_b128 v[96:99], v105
	ds_read_b128 v[106:109], v105 offset:1024
	ds_read_b128 v[110:113], v105 offset:2048
	ds_read_b128 v[114:117], v105 offset:3072
	v_add_u32_e32 v105, s13, v102
	ds_read_b128 v[118:121], v105
	ds_read_b128 v[122:125], v105 offset:1024
	ds_read_b128 v[126:129], v105 offset:2048
	ds_read_b128 v[130:133], v105 offset:3072
	s_add_u32 s0, s22, 0x60000
	s_addc_u32 s1, s23, 0
	s_mov_b32 m0, s37
	v_lshl_add_u64 v[174:175], s[0:1], 0, v[0:1]
	ds_read_b128 v[134:137], v104 offset:32768
	ds_read_b128 v[138:141], v104 offset:33792
	ds_read_b128 v[142:145], v104 offset:34816
	ds_read_b128 v[146:149], v104 offset:35840
	ds_read_b128 v[150:153], v104 offset:36864
	ds_read_b128 v[154:157], v104 offset:37888
	ds_read_b128 v[158:161], v104 offset:38912
	ds_read_b128 v[162:165], v104 offset:39936
	v_lshl_add_u64 v[174:175], s[0:1], 0, v[66:67]
	s_mov_b32 m0, s38
	s_nop 0
	s_waitcnt vmcnt(8)
	s_waitcnt lgkmcnt(0)
	s_barrier
	s_setprio 1
	s_waitcnt lgkmcnt(0)
	v_mfma_f32_16x16x32_bf16 v[62:65], v[96:99], v[134:137], v[62:65]
	v_mfma_f32_16x16x32_bf16 v[58:61], v[110:113], v[134:137], v[58:61]
	v_mfma_f32_16x16x32_bf16 v[46:49], v[96:99], v[142:145], v[46:49]
	v_mfma_f32_16x16x32_bf16 v[42:45], v[110:113], v[142:145], v[42:45]
	v_mfma_f32_16x16x32_bf16 v[30:33], v[96:99], v[150:153], v[30:33]
	v_mfma_f32_16x16x32_bf16 v[26:29], v[110:113], v[150:153], v[26:29]
	v_mfma_f32_16x16x32_bf16 v[14:17], v[96:99], v[158:161], v[14:17]
	v_mfma_f32_16x16x32_bf16 v[10:13], v[110:113], v[158:161], v[10:13]
	v_mfma_f32_16x16x32_bf16 v[62:65], v[106:109], v[138:141], v[62:65]
	v_mfma_f32_16x16x32_bf16 v[58:61], v[114:117], v[138:141], v[58:61]
	v_mfma_f32_16x16x32_bf16 v[46:49], v[106:109], v[146:149], v[46:49]
	v_mfma_f32_16x16x32_bf16 v[42:45], v[114:117], v[146:149], v[42:45]
	v_mfma_f32_16x16x32_bf16 v[30:33], v[106:109], v[154:157], v[30:33]
	v_mfma_f32_16x16x32_bf16 v[26:29], v[114:117], v[154:157], v[26:29]
	v_mfma_f32_16x16x32_bf16 v[14:17], v[106:109], v[162:165], v[14:17]
	v_mfma_f32_16x16x32_bf16 v[10:13], v[114:117], v[162:165], v[10:13]
	s_setprio 0
	s_setprio 1
	v_mfma_f32_16x16x32_bf16 v[54:57], v[118:121], v[134:137], v[54:57]
	v_mfma_f32_16x16x32_bf16 v[50:53], v[126:129], v[134:137], v[50:53]
	v_mfma_f32_16x16x32_bf16 v[38:41], v[118:121], v[142:145], v[38:41]
	v_mfma_f32_16x16x32_bf16 v[34:37], v[126:129], v[142:145], v[34:37]
	v_mfma_f32_16x16x32_bf16 v[22:25], v[118:121], v[150:153], v[22:25]
	v_mfma_f32_16x16x32_bf16 v[18:21], v[126:129], v[150:153], v[18:21]
	v_mfma_f32_16x16x32_bf16 v[6:9], v[118:121], v[158:161], v[6:9]
	v_mfma_f32_16x16x32_bf16 v[2:5], v[126:129], v[158:161], v[2:5]
	v_mfma_f32_16x16x32_bf16 v[54:57], v[122:125], v[138:141], v[54:57]
	v_mfma_f32_16x16x32_bf16 v[50:53], v[130:133], v[138:141], v[50:53]
	v_mfma_f32_16x16x32_bf16 v[38:41], v[122:125], v[146:149], v[38:41]
	v_mfma_f32_16x16x32_bf16 v[34:37], v[130:133], v[146:149], v[34:37]
	v_mfma_f32_16x16x32_bf16 v[22:25], v[122:125], v[154:157], v[22:25]
	v_mfma_f32_16x16x32_bf16 v[18:21], v[130:133], v[154:157], v[18:21]
	v_mfma_f32_16x16x32_bf16 v[6:9], v[122:125], v[162:165], v[6:9]
	v_mfma_f32_16x16x32_bf16 v[2:5], v[130:133], v[162:165], v[2:5]
	s_setprio 0
	s_barrier
	s_add_i32 s0, s12, s34
	v_lshl_add_u64 v[96:97], v[166:167], 0, s[86:87]
	s_mov_b32 m0, s0
	s_nop 0
	global_load_lds_dwordx4 v[96:97], off
	s_add_i32 m0, s0, 0x2000
	s_add_u32 s0, s20, 0x60080
	v_lshl_add_u64 v[96:97], v[168:169], 0, s[86:87]
	s_addc_u32 s1, s21, 0
	s_add_i32 s12, s13, s34
	global_load_lds_dwordx4 v[96:97], off
	v_lshl_add_u64 v[96:97], s[0:1], 0, v[0:1]
	s_mov_b32 m0, s12
	s_nop 0
	global_load_lds_dwordx4 v[96:97], off
	v_lshl_add_u64 v[96:97], s[0:1], 0, v[66:67]
	s_add_i32 m0, s12, 0x2000
	s_nop 0
	global_load_lds_dwordx4 v[96:97], off
	v_lshl_add_u64 v[96:97], v[170:171], 0, s[86:87]
	s_mov_b32 m0, s39
	s_nop 0
	global_load_lds_dwordx4 v[96:97], off
	v_lshl_add_u64 v[96:97], v[172:173], 0, s[86:87]
	s_mov_b32 m0, s40
	s_nop 0
	global_load_lds_dwordx4 v[96:97], off
	s_waitcnt vmcnt(6)
	s_waitcnt lgkmcnt(0)
	s_barrier
	s_barrier
	s_add_i32 s0, s46, 2
	s_add_u32 s18, s18, 0x100
	s_addc_u32 s19, s19, 0
	s_cmp_gt_u32 s46, 21
	s_mov_b32 s46, s0
	s_cbranch_scc1 .LBB0_80

; #define PG8_STAGE(bufoff, gbase, voff) do { _Pragma("unroll") for (int _i = 0; _i < 2; ++_i) \
;         __builtin_amdgcn_global_load_lds((const unsigned*)((const char*)(gbase) + (voff)[_i]), (PG8_LAS unsigned*)(lds + (bufoff) + ldsw + _i * 8192), 16, 0, 0); } while (0)
; #define PG8_LDA(dst, b, h) do { _Pragma("unroll") for (int m = 0; m < 4; ++m) _Pragma("unroll") for (int k = 0; k < 2; ++k) dst[m][k] = *(const PG8_LAS bf16x8*)(lds + PG8_SA(b, h) + aoff + m * 2048 + k * 1024); } while (0)
; #define PG8_LDB(dst, b, h) do { _Pragma("unroll") for (int n = 0; n < 2; ++n) _Pragma("unroll") for (int k = 0; k < 2; ++k) dst[n][k] = *(const PG8_LAS bf16x8*)(lds + PG8_SB(b, h) + boff + n * 2048 + k * 1024); } while (0)
; #define PG8_WAIT_V(n) asm volatile("s_waitcnt vmcnt(" #n ")" ::: "memory")
; #define PG8_WAIT_L(n) asm volatile("s_waitcnt lgkmcnt(" #n ")" ::: "memory")
; #define PG8_BAR __builtin_amdgcn_s_barrier()
; #define PG8_SCHED __builtin_amdgcn_sched_barrier(0)
; template <class Epi, class Sched, bool ALIGN_EPI = false, bool SP2 = false, bool HALFM = false>
; __device__ __forceinline__ void gemm_phase(PG8_LAS unsigned char* lds, const Gemm g, const Sched& S, const Epi& E, const int tid_in) {
;     ...
;         for (int t = 0; t < nt; t += 2) {
;             if constexpr (Epi::KHOOK) { if (t == 8 || t == 16) E.khook(acc, cur, t, wr, wc, fr, fq); }
;             const bool last = (t == nt - 2);
;             const char* a1 = cA + (size_t)(t + 1) * kstep;
;             const char* a2 = last ? nA : cA + (size_t)(t + 2) * kstep; const char* b2 = last ? nB : cB + (size_t)(t + 2) * kstep;
;             const char* a3 = a2 + kstep; const char* b3 = b2 + kstep;
;             if (last && has_next) S.a_ready(nxt);
;             if constexpr (SP2) {
;             PG8_LDB(B0, 0, 0); PG8_LDB(B1, 0, 1); PG8_SCHED; PG8_LDA(At, 0, 0); PG8_STAGE(PG8_SA(1, 1), a1 + hstep, voffA);
;             PG8_WAIT_V(8); PG8_WAIT_L(0); PG8_BAR; PG8_MMA(0, 0, At, B0); PG8_MMA(0, 1, At, B1); PG8_BAR; PG8_SCHED;
;             PG8_LDA(At, 0, 1); PG8_STAGE(PG8_SB(0, 0), b2, voffB); PG8_STAGE(PG8_SB(0, 1), b2 + hstep, voffB); PG8_STAGE(PG8_SA(0, 0), a2, voffA);
;             PG8_WAIT_V(8); PG8_WAIT_L(0); PG8_BAR; if constexpr (!HALFM) { PG8_MMA(1, 0, At, B0); PG8_MMA(1, 1, At, B1); } PG8_BAR; PG8_SCHED;
.LBB0_244:
	s_add_i32 s58, s8, 2
	s_add_u32 s0, s6, 0x80
	s_addc_u32 s1, s7, 0
	s_add_i32 s59, 0, 0x10000
	s_cmp_eq_u32 s29, s8
	s_cselect_b32 s9, s55, s1
	s_cselect_b32 s8, s54, s0
	s_cselect_b32 s1, s57, s11
	s_cselect_b32 s0, s56, s10
	s_add_i32 s89, 0, 0x14000
	v_add_u32_e32 v92, s59, v81
	v_add_u32_e32 v108, s89, v81
	ds_read_b128 v[76:79], v92
	ds_read_b128 v[84:87], v92 offset:1024
	ds_read_b128 v[88:91], v92 offset:2048
	ds_read_b128 v[92:95], v92 offset:3072
	ds_read_b128 v[96:99], v108
	ds_read_b128 v[100:103], v108 offset:1024
	ds_read_b128 v[104:107], v108 offset:2048
	ds_read_b128 v[108:111], v108 offset:3072
	v_lshl_add_u64 v[128:129], s[6:7], 0, v[72:73]
	s_add_i32 m0, s18, 0xc000
	ds_read_b128 v[112:115], v83
	ds_read_b128 v[116:119], v83 offset:1024
	ds_read_b128 v[120:123], v83 offset:2048
	ds_read_b128 v[124:127], v83 offset:3072
	ds_read_b128 v[132:135], v83 offset:4096
	ds_read_b128 v[136:139], v83 offset:5120
	ds_read_b128 v[140:143], v83 offset:6144
	ds_read_b128 v[156:159], v83 offset:7168
	v_lshl_add_u64 v[128:129], s[6:7], 0, v[74:75]
	s_add_i32 m0, s18, 0xe000
	s_nop 0
	s_waitcnt vmcnt(8)
	s_waitcnt lgkmcnt(0)
	s_barrier
	s_setprio 1
	s_waitcnt lgkmcnt(0)
	v_mfma_f32_16x16x32_bf16 v[62:65], v[76:79], v[112:115], v[62:65]
	v_mfma_f32_16x16x32_bf16 v[58:61], v[88:91], v[112:115], v[58:61]
	v_mfma_f32_16x16x32_bf16 v[46:49], v[76:79], v[120:123], v[46:49]
	v_mfma_f32_16x16x32_bf16 v[42:45], v[88:91], v[120:123], v[42:45]
	v_mfma_f32_16x16x32_bf16 v[30:33], v[76:79], v[132:135], v[30:33]
	v_mfma_f32_16x16x32_bf16 v[26:29], v[88:91], v[132:135], v[26:29]
	v_mfma_f32_16x16x32_bf16 v[14:17], v[76:79], v[140:143], v[14:17]
	v_mfma_f32_16x16x32_bf16 v[10:13], v[88:91], v[140:143], v[10:13]
	v_mfma_f32_16x16x32_bf16 v[62:65], v[84:87], v[116:119], v[62:65]
	v_mfma_f32_16x16x32_bf16 v[58:61], v[92:95], v[116:119], v[58:61]
	v_mfma_f32_16x16x32_bf16 v[46:49], v[84:87], v[124:127], v[46:49]
	v_mfma_f32_16x16x32_bf16 v[42:45], v[92:95], v[124:127], v[42:45]
	v_mfma_f32_16x16x32_bf16 v[30:33], v[84:87], v[136:139], v[30:33]
	v_mfma_f32_16x16x32_bf16 v[26:29], v[92:95], v[136:139], v[26:29]
	v_mfma_f32_16x16x32_bf16 v[14:17], v[84:87], v[156:159], v[14:17]
	v_mfma_f32_16x16x32_bf16 v[10:13], v[92:95], v[156:159], v[10:13]
	s_setprio 0
	s_setprio 1
	v_mfma_f32_16x16x32_bf16 v[54:57], v[96:99], v[112:115], v[54:57]
	v_mfma_f32_16x16x32_bf16 v[50:53], v[104:107], v[112:115], v[50:53]
	v_mfma_f32_16x16x32_bf16 v[38:41], v[96:99], v[120:123], v[38:41]
	v_mfma_f32_16x16x32_bf16 v[34:37], v[104:107], v[120:123], v[34:37]
	v_mfma_f32_16x16x32_bf16 v[22:25], v[96:99], v[132:135], v[22:25]
	v_mfma_f32_16x16x32_bf16 v[18:21], v[104:107], v[132:135], v[18:21]
	v_mfma_f32_16x16x32_bf16 v[6:9], v[96:99], v[140:143], v[6:9]
	v_mfma_f32_16x16x32_bf16 v[2:5], v[104:107], v[140:143], v[2:5]
	v_mfma_f32_16x16x32_bf16 v[54:57], v[100:103], v[116:119], v[54:57]
	v_mfma_f32_16x16x32_bf16 v[50:53], v[108:111], v[116:119], v[50:53]
	v_mfma_f32_16x16x32_bf16 v[38:41], v[100:103], v[124:127], v[38:41]
	v_mfma_f32_16x16x32_bf16 v[34:37], v[108:111], v[124:127], v[34:37]
	v_mfma_f32_16x16x32_bf16 v[22:25], v[100:103], v[136:139], v[22:25]
	v_mfma_f32_16x16x32_bf16 v[18:21], v[108:111], v[136:139], v[18:21]
	v_mfma_f32_16x16x32_bf16 v[6:9], v[100:103], v[156:159], v[6:9]
	v_mfma_f32_16x16x32_bf16 v[2:5], v[108:111], v[156:159], v[2:5]
	s_setprio 0
	s_barrier
	s_add_i32 s59, s59, s13
	v_lshl_add_u64 v[128:129], s[0:1], 0, v[0:1]
	s_mov_b32 m0, s59
	v_lshl_add_u64 v[144:145], s[0:1], 0, v[70:71]
	global_load_lds_dwordx4 v[128:129], off
	s_add_i32 m0, s59, 0x2000
	s_add_u32 s0, s0, s92
	s_addc_u32 s1, s1, 0
	s_add_i32 s59, s89, s13
	global_load_lds_dwordx4 v[144:145], off
	v_lshl_add_u64 v[160:161], s[0:1], 0, v[0:1]
	s_mov_b32 m0, s59
	v_lshl_add_u64 v[162:163], s[0:1], 0, v[70:71]
	global_load_lds_dwordx4 v[160:161], off
	s_add_i32 m0, s59, 0x2000
	v_lshl_add_u64 v[164:165], s[8:9], 0, v[66:67]
	global_load_lds_dwordx4 v[162:163], off
	s_mov_b32 m0, s18
	v_lshl_add_u64 v[166:167], s[8:9], 0, v[68:69]
	global_load_lds_dwordx4 v[164:165], off
	s_mov_b32 m0, s19
	s_nop 0
	global_load_lds_dwordx4 v[166:167], off
	s_waitcnt vmcnt(6)
	s_waitcnt lgkmcnt(0)
	s_barrier
	s_barrier
; #define PG8_STAGE(bufoff, gbase, voff) do { _Pragma("unroll") for (int _i = 0; _i < 2; ++_i) \
;         __builtin_amdgcn_global_load_lds((const unsigned*)((const char*)(gbase) + (voff)[_i]), (PG8_LAS unsigned*)(lds + (bufoff) + ldsw + _i * 8192), 16, 0, 0); } while (0)
; #define PG8_LDA(dst, b, h) do { _Pragma("unroll") for (int m = 0; m < 4; ++m) _Pragma("unroll") for (int k = 0; k < 2; ++k) dst[m][k] = *(const PG8_LAS bf16x8*)(lds + PG8_SA(b, h) + aoff + m * 2048 + k * 1024); } while (0)
; #define PG8_LDB(dst, b, h) do { _Pragma("unroll") for (int n = 0; n < 2; ++n) _Pragma("unroll") for (int k = 0; k < 2; ++k) dst[n][k] = *(const PG8_LAS bf16x8*)(lds + PG8_SB(b, h) + boff + n * 2048 + k * 1024); } while (0)
; #define PG8_MMA(ai, bj, At, Bt) do { __builtin_amdgcn_s_setprio(1); _Pragma("unroll") for (int m = 0; m < 4; ++m) _Pragma("unroll") for (int n = 0; n < 2; ++n) _Pragma("unroll") for (int k = 0; k < 2; ++k) \
;         acc[ai][bj][m][n] = __builtin_amdgcn_mfma_f32_16x16x32_bf16(Bt[n][k], At[m][k], acc[ai][bj][m][n], 0, 0, 0); __builtin_amdgcn_s_setprio(0); } while (0)
; #define PG8_WAIT_V(n) asm volatile("s_waitcnt vmcnt(" #n ")" ::: "memory")
; #define PG8_WAIT_L(n) asm volatile("s_waitcnt lgkmcnt(" #n ")" ::: "memory")
; #define PG8_BAR __builtin_amdgcn_s_barrier()
; #define PG8_SCHED __builtin_amdgcn_sched_barrier(0)
; template <class Epi, class Sched, bool ALIGN_EPI = false, bool SP2 = false, bool HALFM = false>
; __device__ __forceinline__ void gemm_phase(PG8_LAS unsigned char* lds, const Gemm g, const Sched& S, const Epi& E, const int tid_in) {
;     ...
;             PG8_LDB(B0, 1, 0); PG8_LDB(B1, 1, 1); PG8_SCHED; PG8_LDA(At, 1, 0); PG8_STAGE(PG8_SA(0, 1), a2 + hstep, voffA);
;             PG8_WAIT_V(8); PG8_WAIT_L(0); PG8_BAR; PG8_MMA(0, 0, At, B0); PG8_MMA(0, 1, At, B1); PG8_BAR; PG8_SCHED;
;             PG8_LDA(At, 1, 1); PG8_STAGE(PG8_SB(1, 0), b3, voffB); PG8_STAGE(PG8_SB(1, 1), b3 + hstep, voffB); PG8_STAGE(PG8_SA(1, 0), a3, voffA);
;             PG8_WAIT_V(8); PG8_WAIT_L(0); PG8_BAR; if constexpr (!HALFM) { PG8_MMA(1, 0, At, B0); PG8_MMA(1, 1, At, B1); } PG8_BAR; PG8_SCHED;
	s_add_i32 s59, 0, 0x18000
	s_add_i32 s89, 0, 0x1c000
	v_add_u32_e32 v92, s59, v81
	v_add_u32_e32 v108, s89, v81
	ds_read_b128 v[76:79], v92
	ds_read_b128 v[84:87], v92 offset:1024
	ds_read_b128 v[88:91], v92 offset:2048
	ds_read_b128 v[92:95], v92 offset:3072
	ds_read_b128 v[96:99], v108
	ds_read_b128 v[100:103], v108 offset:1024
	ds_read_b128 v[104:107], v108 offset:2048
	ds_read_b128 v[108:111], v108 offset:3072
	s_add_u32 s0, s8, s92
	s_addc_u32 s1, s9, 0
	s_mov_b32 m0, s20
	v_lshl_add_u64 v[168:169], s[0:1], 0, v[66:67]
	ds_read_b128 v[112:115], v83 offset:32768
	ds_read_b128 v[116:119], v83 offset:33792
	ds_read_b128 v[120:123], v83 offset:34816
	ds_read_b128 v[124:127], v83 offset:35840
	ds_read_b128 v[132:135], v83 offset:36864
	ds_read_b128 v[136:139], v83 offset:37888
	ds_read_b128 v[140:143], v83 offset:38912
	ds_read_b128 v[156:159], v83 offset:39936
	v_lshl_add_u64 v[168:169], s[0:1], 0, v[68:69]
	s_mov_b32 m0, s21
	s_nop 0
	s_waitcnt vmcnt(8)
	s_waitcnt lgkmcnt(0)
	s_barrier
	s_setprio 1
	s_waitcnt lgkmcnt(0)
	v_mfma_f32_16x16x32_bf16 v[62:65], v[76:79], v[112:115], v[62:65]
	v_mfma_f32_16x16x32_bf16 v[58:61], v[88:91], v[112:115], v[58:61]
	v_mfma_f32_16x16x32_bf16 v[46:49], v[76:79], v[120:123], v[46:49]
	v_mfma_f32_16x16x32_bf16 v[42:45], v[88:91], v[120:123], v[42:45]
	v_mfma_f32_16x16x32_bf16 v[30:33], v[76:79], v[132:135], v[30:33]
	v_mfma_f32_16x16x32_bf16 v[26:29], v[88:91], v[132:135], v[26:29]
	v_mfma_f32_16x16x32_bf16 v[14:17], v[76:79], v[140:143], v[14:17]
	v_mfma_f32_16x16x32_bf16 v[10:13], v[88:91], v[140:143], v[10:13]
	v_mfma_f32_16x16x32_bf16 v[62:65], v[84:87], v[116:119], v[62:65]
	v_mfma_f32_16x16x32_bf16 v[58:61], v[92:95], v[116:119], v[58:61]
	v_mfma_f32_16x16x32_bf16 v[46:49], v[84:87], v[124:127], v[46:49]
	v_mfma_f32_16x16x32_bf16 v[42:45], v[92:95], v[124:127], v[42:45]
	v_mfma_f32_16x16x32_bf16 v[30:33], v[84:87], v[136:139], v[30:33]
	v_mfma_f32_16x16x32_bf16 v[26:29], v[92:95], v[136:139], v[26:29]
	v_mfma_f32_16x16x32_bf16 v[14:17], v[84:87], v[156:159], v[14:17]
	v_mfma_f32_16x16x32_bf16 v[10:13], v[92:95], v[156:159], v[10:13]
	s_setprio 0
	s_setprio 1
	v_mfma_f32_16x16x32_bf16 v[54:57], v[96:99], v[112:115], v[54:57]
	v_mfma_f32_16x16x32_bf16 v[50:53], v[104:107], v[112:115], v[50:53]
	v_mfma_f32_16x16x32_bf16 v[38:41], v[96:99], v[120:123], v[38:41]
	v_mfma_f32_16x16x32_bf16 v[34:37], v[104:107], v[120:123], v[34:37]
	v_mfma_f32_16x16x32_bf16 v[22:25], v[96:99], v[132:135], v[22:25]
	v_mfma_f32_16x16x32_bf16 v[18:21], v[104:107], v[132:135], v[18:21]
	v_mfma_f32_16x16x32_bf16 v[6:9], v[96:99], v[140:143], v[6:9]
	v_mfma_f32_16x16x32_bf16 v[2:5], v[104:107], v[140:143], v[2:5]
	v_mfma_f32_16x16x32_bf16 v[54:57], v[100:103], v[116:119], v[54:57]
	v_mfma_f32_16x16x32_bf16 v[50:53], v[108:111], v[116:119], v[50:53]
	v_mfma_f32_16x16x32_bf16 v[38:41], v[100:103], v[124:127], v[38:41]
	v_mfma_f32_16x16x32_bf16 v[34:37], v[108:111], v[124:127], v[34:37]
	v_mfma_f32_16x16x32_bf16 v[22:25], v[100:103], v[136:139], v[22:25]
	v_mfma_f32_16x16x32_bf16 v[18:21], v[108:111], v[136:139], v[18:21]
	v_mfma_f32_16x16x32_bf16 v[6:9], v[100:103], v[156:159], v[6:9]
	v_mfma_f32_16x16x32_bf16 v[2:5], v[108:111], v[156:159], v[2:5]
	s_setprio 0
	s_barrier
	s_add_i32 s0, s59, s13
	v_lshl_add_u64 v[76:77], v[128:129], 0, s[86:87]
	s_mov_b32 m0, s0
	s_nop 0
	global_load_lds_dwordx4 v[76:77], off
	v_lshl_add_u64 v[76:77], v[144:145], 0, s[86:87]
	s_add_i32 m0, s0, 0x2000
	s_add_i32 s0, s89, s13
	global_load_lds_dwordx4 v[76:77], off
	v_lshl_add_u64 v[76:77], v[160:161], 0, s[86:87]
	s_mov_b32 m0, s0
	s_nop 0
	global_load_lds_dwordx4 v[76:77], off
	v_lshl_add_u64 v[76:77], v[162:163], 0, s[86:87]
	s_add_i32 m0, s0, 0x2000
	s_nop 0
	global_load_lds_dwordx4 v[76:77], off
	v_lshl_add_u64 v[76:77], v[164:165], 0, s[86:87]
	s_mov_b32 m0, s22
	s_nop 0
	global_load_lds_dwordx4 v[76:77], off
	v_lshl_add_u64 v[76:77], v[166:167], 0, s[86:87]
	s_mov_b32 m0, s23
	s_nop 0
	global_load_lds_dwordx4 v[76:77], off
	s_waitcnt vmcnt(6)
	s_waitcnt lgkmcnt(0)
	s_barrier
	s_barrier
	s_add_u32 s6, s6, 0x100
	s_addc_u32 s7, s7, 0
	s_add_u32 s10, s10, 0x100
	s_addc_u32 s11, s11, 0
	s_cmp_ge_u32 s58, s28
	s_mov_b32 s8, s58
	s_cbranch_scc0 .LBB0_244
	s_and_b64 vcc, exec, s[52:53]
	s_cbranch_vccz .LBB0_247
	s_barrier

; #define PG8_STAGE(bufoff, gbase, voff) do { _Pragma("unroll") for (int _i = 0; _i < 2; ++_i) \
;         __builtin_amdgcn_global_load_lds((const unsigned*)((const char*)(gbase) + (voff)[_i]), (PG8_LAS unsigned*)(lds + (bufoff) + ldsw + _i * 8192), 16, 0, 0); } while (0)
; #define PG8_LDA(dst, b, h) do { _Pragma("unroll") for (int m = 0; m < 4; ++m) _Pragma("unroll") for (int k = 0; k < 2; ++k) dst[m][k] = *(const PG8_LAS bf16x8*)(lds + PG8_SA(b, h) + aoff + m * 2048 + k * 1024); } while (0)
; #define PG8_LDB(dst, b, h) do { _Pragma("unroll") for (int n = 0; n < 2; ++n) _Pragma("unroll") for (int k = 0; k < 2; ++k) dst[n][k] = *(const PG8_LAS bf16x8*)(lds + PG8_SB(b, h) + boff + n * 2048 + k * 1024); } while (0)
; #define PG8_WAIT_V(n) asm volatile("s_waitcnt vmcnt(" #n ")" ::: "memory")
; #define PG8_WAIT_L(n) asm volatile("s_waitcnt lgkmcnt(" #n ")" ::: "memory")
; #define PG8_BAR __builtin_amdgcn_s_barrier()
; #define PG8_SCHED __builtin_amdgcn_sched_barrier(0)
; template <class Epi, class Sched, bool ALIGN_EPI = false, bool SP2 = false, bool HALFM = false>
; __device__ __forceinline__ void gemm_phase(PG8_LAS unsigned char* lds, const Gemm g, const Sched& S, const Epi& E, const int tid_in) {
;     ...
;         for (int t = 0; t < nt; t += 2) {
;             if constexpr (Epi::KHOOK) { if (t == 8 || t == 16) E.khook(acc, cur, t, wr, wc, fr, fq); }
;             const bool last = (t == nt - 2);
;             const char* a1 = cA + (size_t)(t + 1) * kstep;
;             const char* a2 = last ? nA : cA + (size_t)(t + 2) * kstep; const char* b2 = last ? nB : cB + (size_t)(t + 2) * kstep;
;             const char* a3 = a2 + kstep; const char* b3 = b2 + kstep;
;             if (last && has_next) S.a_ready(nxt);
;             if constexpr (SP2) {
;             PG8_LDB(B0, 0, 0); PG8_LDB(B1, 0, 1); PG8_SCHED; PG8_LDA(At, 0, 0); PG8_STAGE(PG8_SA(1, 1), a1 + hstep, voffA);
;             PG8_WAIT_V(8); PG8_WAIT_L(0); PG8_BAR; PG8_MMA(0, 0, At, B0); PG8_MMA(0, 1, At, B1); PG8_BAR; PG8_SCHED;
;             PG8_LDA(At, 0, 1); PG8_STAGE(PG8_SB(0, 0), b2, voffB); PG8_STAGE(PG8_SB(0, 1), b2 + hstep, voffB); PG8_STAGE(PG8_SA(0, 0), a2, voffA);
;             PG8_WAIT_V(8); PG8_WAIT_L(0); PG8_BAR; if constexpr (!HALFM) { PG8_MMA(1, 0, At, B0); PG8_MMA(1, 1, At, B1); } PG8_BAR; PG8_SCHED;
.LBB0_352:
	s_add_u32 s0, s24, 0xfffc0080
	s_addc_u32 s1, s25, -1
	s_add_i32 s49, 0, 0x10000
	s_cmp_eq_u32 s48, 12
	s_cselect_b32 s29, s17, s1
	s_cselect_b32 s28, s44, s0
	v_add_u32_e32 v70, s49, v73
	s_cselect_b32 s27, s15, s47
	s_cselect_b32 s26, s45, s46
	s_add_i32 s50, 0, 0x14000
	ds_read_b128 v[80:83], v70
	ds_read_b128 v[84:87], v70 offset:1024
	ds_read_b128 v[88:91], v70 offset:2048
	ds_read_b128 v[92:95], v70 offset:3072
	v_add_u32_e32 v70, s50, v73
	ds_read_b128 v[96:99], v70
	ds_read_b128 v[100:103], v70 offset:1024
	ds_read_b128 v[104:107], v70 offset:2048
	ds_read_b128 v[108:111], v70 offset:3072
	v_lshl_add_u64 v[70:71], s[24:25], 0, v[68:69]
	s_add_i32 m0, s37, 0xc000
	ds_read_b128 v[112:115], v78
	ds_read_b128 v[116:119], v78 offset:1024
	ds_read_b128 v[120:123], v78 offset:2048
	ds_read_b128 v[124:127], v78 offset:3072
	ds_read_b128 v[132:135], v78 offset:4096
	ds_read_b128 v[136:139], v78 offset:5120
	ds_read_b128 v[140:143], v78 offset:6144
	ds_read_b128 v[144:147], v78 offset:7168
	v_lshl_add_u64 v[70:71], s[24:25], 0, v[66:67]
	s_add_i32 m0, s37, 0xe000
	s_nop 0
	s_waitcnt vmcnt(8)
	s_waitcnt lgkmcnt(0)
	s_barrier
	s_setprio 1
	s_waitcnt lgkmcnt(0)
	v_mfma_f32_16x16x32_bf16 v[62:65], v[80:83], v[112:115], v[62:65]
	v_mfma_f32_16x16x32_bf16 v[58:61], v[88:91], v[112:115], v[58:61]
	v_mfma_f32_16x16x32_bf16 v[46:49], v[80:83], v[120:123], v[46:49]
	v_mfma_f32_16x16x32_bf16 v[42:45], v[88:91], v[120:123], v[42:45]
	v_mfma_f32_16x16x32_bf16 v[30:33], v[80:83], v[132:135], v[30:33]
	v_mfma_f32_16x16x32_bf16 v[26:29], v[88:91], v[132:135], v[26:29]
	v_mfma_f32_16x16x32_bf16 v[14:17], v[80:83], v[140:143], v[14:17]
	v_mfma_f32_16x16x32_bf16 v[10:13], v[88:91], v[140:143], v[10:13]
	v_mfma_f32_16x16x32_bf16 v[62:65], v[84:87], v[116:119], v[62:65]
	v_mfma_f32_16x16x32_bf16 v[58:61], v[92:95], v[116:119], v[58:61]
	v_mfma_f32_16x16x32_bf16 v[46:49], v[84:87], v[124:127], v[46:49]
	v_mfma_f32_16x16x32_bf16 v[42:45], v[92:95], v[124:127], v[42:45]
	v_mfma_f32_16x16x32_bf16 v[30:33], v[84:87], v[136:139], v[30:33]
	v_mfma_f32_16x16x32_bf16 v[26:29], v[92:95], v[136:139], v[26:29]
	v_mfma_f32_16x16x32_bf16 v[14:17], v[84:87], v[144:147], v[14:17]
	v_mfma_f32_16x16x32_bf16 v[10:13], v[92:95], v[144:147], v[10:13]
	s_setprio 0
	s_setprio 1
	v_mfma_f32_16x16x32_bf16 v[54:57], v[96:99], v[112:115], v[54:57]
	v_mfma_f32_16x16x32_bf16 v[50:53], v[104:107], v[112:115], v[50:53]
	v_mfma_f32_16x16x32_bf16 v[38:41], v[96:99], v[120:123], v[38:41]
	v_mfma_f32_16x16x32_bf16 v[34:37], v[104:107], v[120:123], v[34:37]
	v_mfma_f32_16x16x32_bf16 v[22:25], v[96:99], v[132:135], v[22:25]
	v_mfma_f32_16x16x32_bf16 v[18:21], v[104:107], v[132:135], v[18:21]
	v_mfma_f32_16x16x32_bf16 v[6:9], v[96:99], v[140:143], v[6:9]
	v_mfma_f32_16x16x32_bf16 v[2:5], v[104:107], v[140:143], v[2:5]
	v_mfma_f32_16x16x32_bf16 v[54:57], v[100:103], v[116:119], v[54:57]
	v_mfma_f32_16x16x32_bf16 v[50:53], v[108:111], v[116:119], v[50:53]
	v_mfma_f32_16x16x32_bf16 v[38:41], v[100:103], v[124:127], v[38:41]
	v_mfma_f32_16x16x32_bf16 v[34:37], v[108:111], v[124:127], v[34:37]
	v_mfma_f32_16x16x32_bf16 v[22:25], v[100:103], v[136:139], v[22:25]
	v_mfma_f32_16x16x32_bf16 v[18:21], v[108:111], v[136:139], v[18:21]
	v_mfma_f32_16x16x32_bf16 v[6:9], v[100:103], v[144:147], v[6:9]
	v_mfma_f32_16x16x32_bf16 v[2:5], v[108:111], v[144:147], v[2:5]
	s_setprio 0
	s_barrier
	s_add_i32 s0, s49, s36
	v_lshl_add_u64 v[70:71], s[26:27], 0, v[0:1]
	s_mov_b32 m0, s0
	v_lshl_add_u64 v[128:129], s[26:27], 0, v[66:67]
	global_load_lds_dwordx4 v[70:71], off
	s_add_i32 m0, s0, 0x2000
	s_add_u32 s0, s26, 0x40000
	s_addc_u32 s1, s27, 0
	s_add_i32 s49, s50, s36
	global_load_lds_dwordx4 v[128:129], off
	v_lshl_add_u64 v[80:81], s[0:1], 0, v[0:1]
	s_mov_b32 m0, s49
	v_lshl_add_u64 v[148:149], s[28:29], 0, v[0:1]
	global_load_lds_dwordx4 v[80:81], off
	v_lshl_add_u64 v[80:81], s[0:1], 0, v[66:67]
	s_add_i32 m0, s49, 0x2000
	v_lshl_add_u64 v[150:151], s[28:29], 0, v[66:67]
	global_load_lds_dwordx4 v[80:81], off
	s_mov_b32 m0, s37
	s_nop 0
	global_load_lds_dwordx4 v[148:149], off
	s_mov_b32 m0, s38
	s_nop 0
	global_load_lds_dwordx4 v[150:151], off
	s_waitcnt vmcnt(6)
	s_waitcnt lgkmcnt(0)
	s_barrier
	s_barrier
; #define PG8_STAGE(bufoff, gbase, voff) do { _Pragma("unroll") for (int _i = 0; _i < 2; ++_i) \
;         __builtin_amdgcn_global_load_lds((const unsigned*)((const char*)(gbase) + (voff)[_i]), (PG8_LAS unsigned*)(lds + (bufoff) + ldsw + _i * 8192), 16, 0, 0); } while (0)
; #define PG8_LDA(dst, b, h) do { _Pragma("unroll") for (int m = 0; m < 4; ++m) _Pragma("unroll") for (int k = 0; k < 2; ++k) dst[m][k] = *(const PG8_LAS bf16x8*)(lds + PG8_SA(b, h) + aoff + m * 2048 + k * 1024); } while (0)
; #define PG8_LDB(dst, b, h) do { _Pragma("unroll") for (int n = 0; n < 2; ++n) _Pragma("unroll") for (int k = 0; k < 2; ++k) dst[n][k] = *(const PG8_LAS bf16x8*)(lds + PG8_SB(b, h) + boff + n * 2048 + k * 1024); } while (0)
; #define PG8_MMA(ai, bj, At, Bt) do { __builtin_amdgcn_s_setprio(1); _Pragma("unroll") for (int m = 0; m < 4; ++m) _Pragma("unroll") for (int n = 0; n < 2; ++n) _Pragma("unroll") for (int k = 0; k < 2; ++k) \
;         acc[ai][bj][m][n] = __builtin_amdgcn_mfma_f32_16x16x32_bf16(Bt[n][k], At[m][k], acc[ai][bj][m][n], 0, 0, 0); __builtin_amdgcn_s_setprio(0); } while (0)
; #define PG8_WAIT_V(n) asm volatile("s_waitcnt vmcnt(" #n ")" ::: "memory")
; #define PG8_WAIT_L(n) asm volatile("s_waitcnt lgkmcnt(" #n ")" ::: "memory")
; #define PG8_BAR __builtin_amdgcn_s_barrier()
; #define PG8_SCHED __builtin_amdgcn_sched_barrier(0)
; template <class Epi, class Sched, bool ALIGN_EPI = false, bool SP2 = false, bool HALFM = false>
; __device__ __forceinline__ void gemm_phase(PG8_LAS unsigned char* lds, const Gemm g, const Sched& S, const Epi& E, const int tid_in) {
;     ...
;             PG8_LDB(B0, 1, 0); PG8_LDB(B1, 1, 1); PG8_SCHED; PG8_LDA(At, 1, 0); PG8_STAGE(PG8_SA(0, 1), a2 + hstep, voffA);
;             PG8_WAIT_V(8); PG8_WAIT_L(0); PG8_BAR; PG8_MMA(0, 0, At, B0); PG8_MMA(0, 1, At, B1); PG8_BAR; PG8_SCHED;
;             PG8_LDA(At, 1, 1); PG8_STAGE(PG8_SB(1, 0), b3, voffB); PG8_STAGE(PG8_SB(1, 1), b3 + hstep, voffB); PG8_STAGE(PG8_SA(1, 0), a3, voffA);
;             PG8_WAIT_V(8); PG8_WAIT_L(0); PG8_BAR; if constexpr (!HALFM) { PG8_MMA(1, 0, At, B0); PG8_MMA(1, 1, At, B1); } PG8_BAR; PG8_SCHED;
	s_add_i32 s49, 0, 0x18000
	v_add_u32_e32 v79, s49, v73
	s_add_i32 s50, 0, 0x1c000
	ds_read_b128 v[80:83], v79
	ds_read_b128 v[84:87], v79 offset:1024
	ds_read_b128 v[88:91], v79 offset:2048
	ds_read_b128 v[92:95], v79 offset:3072
	v_add_u32_e32 v79, s50, v73
	ds_read_b128 v[96:99], v79
	ds_read_b128 v[100:103], v79 offset:1024
	ds_read_b128 v[104:107], v79 offset:2048
	ds_read_b128 v[108:111], v79 offset:3072
	s_add_u32 s0, s28, 0x40000
	s_addc_u32 s1, s29, 0
	s_mov_b32 m0, s39
	v_lshl_add_u64 v[152:153], s[0:1], 0, v[0:1]
	ds_read_b128 v[112:115], v78 offset:32768
	ds_read_b128 v[116:119], v78 offset:33792
	ds_read_b128 v[120:123], v78 offset:34816
	ds_read_b128 v[124:127], v78 offset:35840
	ds_read_b128 v[132:135], v78 offset:36864
	ds_read_b128 v[136:139], v78 offset:37888
	ds_read_b128 v[140:143], v78 offset:38912
	ds_read_b128 v[144:147], v78 offset:39936
	v_lshl_add_u64 v[152:153], s[0:1], 0, v[66:67]
	s_mov_b32 m0, s40
	s_nop 0
	s_waitcnt vmcnt(8)
	s_waitcnt lgkmcnt(0)
	s_barrier
	s_setprio 1
	s_waitcnt lgkmcnt(0)
	v_mfma_f32_16x16x32_bf16 v[62:65], v[80:83], v[112:115], v[62:65]
	v_mfma_f32_16x16x32_bf16 v[58:61], v[88:91], v[112:115], v[58:61]
	v_mfma_f32_16x16x32_bf16 v[46:49], v[80:83], v[120:123], v[46:49]
	v_mfma_f32_16x16x32_bf16 v[42:45], v[88:91], v[120:123], v[42:45]
	v_mfma_f32_16x16x32_bf16 v[30:33], v[80:83], v[132:135], v[30:33]
	v_mfma_f32_16x16x32_bf16 v[26:29], v[88:91], v[132:135], v[26:29]
	v_mfma_f32_16x16x32_bf16 v[14:17], v[80:83], v[140:143], v[14:17]
	v_mfma_f32_16x16x32_bf16 v[10:13], v[88:91], v[140:143], v[10:13]
	v_mfma_f32_16x16x32_bf16 v[62:65], v[84:87], v[116:119], v[62:65]
	v_mfma_f32_16x16x32_bf16 v[58:61], v[92:95], v[116:119], v[58:61]
	v_mfma_f32_16x16x32_bf16 v[46:49], v[84:87], v[124:127], v[46:49]
	v_mfma_f32_16x16x32_bf16 v[42:45], v[92:95], v[124:127], v[42:45]
	v_mfma_f32_16x16x32_bf16 v[30:33], v[84:87], v[136:139], v[30:33]
	v_mfma_f32_16x16x32_bf16 v[26:29], v[92:95], v[136:139], v[26:29]
	v_mfma_f32_16x16x32_bf16 v[14:17], v[84:87], v[144:147], v[14:17]
	v_mfma_f32_16x16x32_bf16 v[10:13], v[92:95], v[144:147], v[10:13]
	s_setprio 0
	s_setprio 1
	v_mfma_f32_16x16x32_bf16 v[54:57], v[96:99], v[112:115], v[54:57]
	v_mfma_f32_16x16x32_bf16 v[50:53], v[104:107], v[112:115], v[50:53]
	v_mfma_f32_16x16x32_bf16 v[38:41], v[96:99], v[120:123], v[38:41]
	v_mfma_f32_16x16x32_bf16 v[34:37], v[104:107], v[120:123], v[34:37]
	v_mfma_f32_16x16x32_bf16 v[22:25], v[96:99], v[132:135], v[22:25]
	v_mfma_f32_16x16x32_bf16 v[18:21], v[104:107], v[132:135], v[18:21]
	v_mfma_f32_16x16x32_bf16 v[6:9], v[96:99], v[140:143], v[6:9]
	v_mfma_f32_16x16x32_bf16 v[2:5], v[104:107], v[140:143], v[2:5]
	v_mfma_f32_16x16x32_bf16 v[54:57], v[100:103], v[116:119], v[54:57]
	v_mfma_f32_16x16x32_bf16 v[50:53], v[108:111], v[116:119], v[50:53]
	v_mfma_f32_16x16x32_bf16 v[38:41], v[100:103], v[124:127], v[38:41]
	v_mfma_f32_16x16x32_bf16 v[34:37], v[108:111], v[124:127], v[34:37]
	v_mfma_f32_16x16x32_bf16 v[22:25], v[100:103], v[136:139], v[22:25]
	v_mfma_f32_16x16x32_bf16 v[18:21], v[108:111], v[136:139], v[18:21]
	v_mfma_f32_16x16x32_bf16 v[6:9], v[100:103], v[144:147], v[6:9]
	v_mfma_f32_16x16x32_bf16 v[2:5], v[108:111], v[144:147], v[2:5]
	s_setprio 0
	s_barrier
	s_add_i32 s0, s49, s36
	v_lshl_add_u64 v[70:71], v[70:71], 0, s[86:87]
	s_mov_b32 m0, s0
	s_nop 0
	global_load_lds_dwordx4 v[70:71], off
	s_add_i32 m0, s0, 0x2000
	s_add_u32 s0, s26, 0x40080
	v_lshl_add_u64 v[70:71], v[128:129], 0, s[86:87]
	s_addc_u32 s1, s27, 0
	s_add_i32 s26, s50, s36
	global_load_lds_dwordx4 v[70:71], off
	v_lshl_add_u64 v[70:71], s[0:1], 0, v[0:1]
	s_mov_b32 m0, s26
	s_nop 0
	global_load_lds_dwordx4 v[70:71], off
	v_lshl_add_u64 v[70:71], s[0:1], 0, v[66:67]
	s_add_i32 m0, s26, 0x2000
	s_nop 0
	global_load_lds_dwordx4 v[70:71], off
	v_lshl_add_u64 v[70:71], v[148:149], 0, s[86:87]
	s_mov_b32 m0, s41
	s_nop 0
	global_load_lds_dwordx4 v[70:71], off
	v_lshl_add_u64 v[70:71], v[150:151], 0, s[86:87]
	s_mov_b32 m0, s42
	s_nop 0
	global_load_lds_dwordx4 v[70:71], off
	s_waitcnt vmcnt(6)
	s_waitcnt lgkmcnt(0)
	s_barrier
	s_barrier
	s_add_i32 s48, s48, 2
	s_add_u32 s24, s24, 0x100
	s_addc_u32 s25, s25, 0
	s_add_u32 s46, s46, 0x100
	s_addc_u32 s47, s47, 0
	s_cmp_gt_u32 s48, 13
	s_cbranch_scc0 .LBB0_352
	s_and_b64 vcc, exec, s[10:11]
	s_cbranch_vccz .LBB0_355
	s_barrier

; #define PG8_STAGE(bufoff, gbase, voff) do { _Pragma("unroll") for (int _i = 0; _i < 2; ++_i) \
;         __builtin_amdgcn_global_load_lds((const unsigned*)((const char*)(gbase) + (voff)[_i]), (PG8_LAS unsigned*)(lds + (bufoff) + ldsw + _i * 8192), 16, 0, 0); } while (0)
; #define PG8_LDA(dst, b, h) do { _Pragma("unroll") for (int m = 0; m < 4; ++m) _Pragma("unroll") for (int k = 0; k < 2; ++k) dst[m][k] = *(const PG8_LAS bf16x8*)(lds + PG8_SA(b, h) + aoff + m * 2048 + k * 1024); } while (0)
; #define PG8_LDB(dst, b, h) do { _Pragma("unroll") for (int n = 0; n < 2; ++n) _Pragma("unroll") for (int k = 0; k < 2; ++k) dst[n][k] = *(const PG8_LAS bf16x8*)(lds + PG8_SB(b, h) + boff + n * 2048 + k * 1024); } while (0)
; #define PG8_WAIT_V(n) asm volatile("s_waitcnt vmcnt(" #n ")" ::: "memory")
; #define PG8_WAIT_L(n) asm volatile("s_waitcnt lgkmcnt(" #n ")" ::: "memory")
; #define PG8_BAR __builtin_amdgcn_s_barrier()
; #define PG8_SCHED __builtin_amdgcn_sched_barrier(0)
; template <class Epi, class Sched, bool ALIGN_EPI = false, bool SP2 = false, bool HALFM = false>
; __device__ __forceinline__ void gemm_phase(PG8_LAS unsigned char* lds, const Gemm g, const Sched& S, const Epi& E, const int tid_in) {
;     ...
;         for (int t = 0; t < nt; t += 2) {
;             if constexpr (Epi::KHOOK) { if (t == 8 || t == 16) E.khook(acc, cur, t, wr, wc, fr, fq); }
;             const bool last = (t == nt - 2);
;             const char* a1 = cA + (size_t)(t + 1) * kstep;
;             const char* a2 = last ? nA : cA + (size_t)(t + 2) * kstep; const char* b2 = last ? nB : cB + (size_t)(t + 2) * kstep;
;             const char* a3 = a2 + kstep; const char* b3 = b2 + kstep;
;             if (last && has_next) S.a_ready(nxt);
;             if constexpr (SP2) {
;             PG8_LDB(B0, 0, 0); PG8_LDB(B1, 0, 1); PG8_SCHED; PG8_LDA(At, 0, 0); PG8_STAGE(PG8_SA(1, 1), a1 + hstep, voffA);
;             PG8_WAIT_V(8); PG8_WAIT_L(0); PG8_BAR; PG8_MMA(0, 0, At, B0); PG8_MMA(0, 1, At, B1); PG8_BAR; PG8_SCHED;
;             PG8_LDA(At, 0, 1); PG8_STAGE(PG8_SB(0, 0), b2, voffB); PG8_STAGE(PG8_SB(0, 1), b2 + hstep, voffB); PG8_STAGE(PG8_SA(0, 0), a2, voffA);
;             PG8_WAIT_V(8); PG8_WAIT_L(0); PG8_BAR; if constexpr (!HALFM) { PG8_MMA(1, 0, At, B0); PG8_MMA(1, 1, At, B1); } PG8_BAR; PG8_SCHED;
.LBB0_419:
	s_add_u32 s0, s22, 0xfffc0080
	s_addc_u32 s1, s23, -1
	s_add_i32 s47, 0, 0x10000
	s_cmp_eq_u32 s46, 12
	s_cselect_b32 s27, s15, s1
	s_cselect_b32 s26, s42, s0
	v_add_u32_e32 v70, s47, v73
	s_cselect_b32 s25, s13, s45
	s_cselect_b32 s24, s43, s44
	s_add_i32 s48, 0, 0x14000
	ds_read_b128 v[76:79], v70
	ds_read_b128 v[80:83], v70 offset:1024
	ds_read_b128 v[84:87], v70 offset:2048
	ds_read_b128 v[88:91], v70 offset:3072
	v_add_u32_e32 v70, s48, v73
	ds_read_b128 v[92:95], v70
	ds_read_b128 v[96:99], v70 offset:1024
	ds_read_b128 v[100:103], v70 offset:2048
	ds_read_b128 v[104:107], v70 offset:3072
	v_lshl_add_u64 v[70:71], s[22:23], 0, v[66:67]
	s_add_i32 m0, s35, 0xc000
	ds_read_b128 v[108:111], v75
	ds_read_b128 v[112:115], v75 offset:1024
	ds_read_b128 v[116:119], v75 offset:2048
	ds_read_b128 v[120:123], v75 offset:3072
	ds_read_b128 v[124:127], v75 offset:4096
	ds_read_b128 v[136:139], v75 offset:5120
	ds_read_b128 v[144:147], v75 offset:6144
	ds_read_b128 v[148:151], v75 offset:7168
	v_lshl_add_u64 v[70:71], s[22:23], 0, v[68:69]
	s_add_i32 m0, s35, 0xe000
	s_nop 0
	s_waitcnt vmcnt(8)
	s_waitcnt lgkmcnt(0)
	s_barrier
	s_setprio 1
	s_waitcnt lgkmcnt(0)
	v_mfma_f32_16x16x32_bf16 v[62:65], v[76:79], v[108:111], v[62:65]
	v_mfma_f32_16x16x32_bf16 v[54:57], v[84:87], v[108:111], v[54:57]
	v_mfma_f32_16x16x32_bf16 v[46:49], v[76:79], v[116:119], v[46:49]
	v_mfma_f32_16x16x32_bf16 v[38:41], v[84:87], v[116:119], v[38:41]
	v_mfma_f32_16x16x32_bf16 v[30:33], v[76:79], v[124:127], v[30:33]
	v_mfma_f32_16x16x32_bf16 v[22:25], v[84:87], v[124:127], v[22:25]
	v_mfma_f32_16x16x32_bf16 v[14:17], v[76:79], v[144:147], v[14:17]
	v_mfma_f32_16x16x32_bf16 v[6:9], v[84:87], v[144:147], v[6:9]
	v_mfma_f32_16x16x32_bf16 v[62:65], v[80:83], v[112:115], v[62:65]
	v_mfma_f32_16x16x32_bf16 v[54:57], v[88:91], v[112:115], v[54:57]
	v_mfma_f32_16x16x32_bf16 v[46:49], v[80:83], v[120:123], v[46:49]
	v_mfma_f32_16x16x32_bf16 v[38:41], v[88:91], v[120:123], v[38:41]
	v_mfma_f32_16x16x32_bf16 v[30:33], v[80:83], v[136:139], v[30:33]
	v_mfma_f32_16x16x32_bf16 v[22:25], v[88:91], v[136:139], v[22:25]
	v_mfma_f32_16x16x32_bf16 v[14:17], v[80:83], v[148:151], v[14:17]
	v_mfma_f32_16x16x32_bf16 v[6:9], v[88:91], v[148:151], v[6:9]
	s_setprio 0
	s_setprio 1
	v_mfma_f32_16x16x32_bf16 v[58:61], v[92:95], v[108:111], v[58:61]
	v_mfma_f32_16x16x32_bf16 v[50:53], v[100:103], v[108:111], v[50:53]
	v_mfma_f32_16x16x32_bf16 v[42:45], v[92:95], v[116:119], v[42:45]
	v_mfma_f32_16x16x32_bf16 v[34:37], v[100:103], v[116:119], v[34:37]
	v_mfma_f32_16x16x32_bf16 v[26:29], v[92:95], v[124:127], v[26:29]
	v_mfma_f32_16x16x32_bf16 v[18:21], v[100:103], v[124:127], v[18:21]
	v_mfma_f32_16x16x32_bf16 v[10:13], v[92:95], v[144:147], v[10:13]
	v_mfma_f32_16x16x32_bf16 v[2:5], v[100:103], v[144:147], v[2:5]
	v_mfma_f32_16x16x32_bf16 v[58:61], v[96:99], v[112:115], v[58:61]
	v_mfma_f32_16x16x32_bf16 v[50:53], v[104:107], v[112:115], v[50:53]
	v_mfma_f32_16x16x32_bf16 v[42:45], v[96:99], v[120:123], v[42:45]
	v_mfma_f32_16x16x32_bf16 v[34:37], v[104:107], v[120:123], v[34:37]
	v_mfma_f32_16x16x32_bf16 v[26:29], v[96:99], v[136:139], v[26:29]
	v_mfma_f32_16x16x32_bf16 v[18:21], v[104:107], v[136:139], v[18:21]
	v_mfma_f32_16x16x32_bf16 v[10:13], v[96:99], v[148:151], v[10:13]
	v_mfma_f32_16x16x32_bf16 v[2:5], v[104:107], v[148:151], v[2:5]
	s_setprio 0
	s_barrier
	s_add_i32 s0, s47, s34
	v_lshl_add_u64 v[70:71], s[24:25], 0, v[0:1]
	s_mov_b32 m0, s0
	v_lshl_add_u64 v[128:129], s[24:25], 0, v[134:135]
	global_load_lds_dwordx4 v[70:71], off
	s_add_i32 m0, s0, 0x2000
	s_add_u32 s0, s24, 0x40000
	s_addc_u32 s1, s25, 0
	s_add_i32 s47, s48, s34
	global_load_lds_dwordx4 v[128:129], off
	v_lshl_add_u64 v[76:77], s[0:1], 0, v[0:1]
	s_mov_b32 m0, s47
	v_lshl_add_u64 v[140:141], s[26:27], 0, v[130:131]
	global_load_lds_dwordx4 v[76:77], off
	v_lshl_add_u64 v[76:77], s[0:1], 0, v[134:135]
	s_add_i32 m0, s47, 0x2000
	v_lshl_add_u64 v[152:153], s[26:27], 0, v[132:133]
	global_load_lds_dwordx4 v[76:77], off
	s_mov_b32 m0, s35
	s_nop 0
	global_load_lds_dwordx4 v[140:141], off
	s_mov_b32 m0, s36
	s_nop 0
	global_load_lds_dwordx4 v[152:153], off
	s_waitcnt vmcnt(6)
	s_waitcnt lgkmcnt(0)
	s_barrier
	s_barrier
; #define PG8_STAGE(bufoff, gbase, voff) do { _Pragma("unroll") for (int _i = 0; _i < 2; ++_i) \
;         __builtin_amdgcn_global_load_lds((const unsigned*)((const char*)(gbase) + (voff)[_i]), (PG8_LAS unsigned*)(lds + (bufoff) + ldsw + _i * 8192), 16, 0, 0); } while (0)
; #define PG8_LDA(dst, b, h) do { _Pragma("unroll") for (int m = 0; m < 4; ++m) _Pragma("unroll") for (int k = 0; k < 2; ++k) dst[m][k] = *(const PG8_LAS bf16x8*)(lds + PG8_SA(b, h) + aoff + m * 2048 + k * 1024); } while (0)
; #define PG8_LDB(dst, b, h) do { _Pragma("unroll") for (int n = 0; n < 2; ++n) _Pragma("unroll") for (int k = 0; k < 2; ++k) dst[n][k] = *(const PG8_LAS bf16x8*)(lds + PG8_SB(b, h) + boff + n * 2048 + k * 1024); } while (0)
; #define PG8_MMA(ai, bj, At, Bt) do { __builtin_amdgcn_s_setprio(1); _Pragma("unroll") for (int m = 0; m < 4; ++m) _Pragma("unroll") for (int n = 0; n < 2; ++n) _Pragma("unroll") for (int k = 0; k < 2; ++k) \
;         acc[ai][bj][m][n] = __builtin_amdgcn_mfma_f32_16x16x32_bf16(Bt[n][k], At[m][k], acc[ai][bj][m][n], 0, 0, 0); __builtin_amdgcn_s_setprio(0); } while (0)
; #define PG8_WAIT_V(n) asm volatile("s_waitcnt vmcnt(" #n ")" ::: "memory")
; #define PG8_WAIT_L(n) asm volatile("s_waitcnt lgkmcnt(" #n ")" ::: "memory")
; #define PG8_BAR __builtin_amdgcn_s_barrier()
; #define PG8_SCHED __builtin_amdgcn_sched_barrier(0)
; template <class Epi, class Sched, bool ALIGN_EPI = false, bool SP2 = false, bool HALFM = false>
; __device__ __forceinline__ void gemm_phase(PG8_LAS unsigned char* lds, const Gemm g, const Sched& S, const Epi& E, const int tid_in) {
;     ...
;             PG8_LDB(B0, 1, 0); PG8_LDB(B1, 1, 1); PG8_SCHED; PG8_LDA(At, 1, 0); PG8_STAGE(PG8_SA(0, 1), a2 + hstep, voffA);
;             PG8_WAIT_V(8); PG8_WAIT_L(0); PG8_BAR; PG8_MMA(0, 0, At, B0); PG8_MMA(0, 1, At, B1); PG8_BAR; PG8_SCHED;
;             PG8_LDA(At, 1, 1); PG8_STAGE(PG8_SB(1, 0), b3, voffB); PG8_STAGE(PG8_SB(1, 1), b3 + hstep, voffB); PG8_STAGE(PG8_SA(1, 0), a3, voffA);
;             PG8_WAIT_V(8); PG8_WAIT_L(0); PG8_BAR; if constexpr (!HALFM) { PG8_MMA(1, 0, At, B0); PG8_MMA(1, 1, At, B1); } PG8_BAR; PG8_SCHED;
	s_add_i32 s47, 0, 0x18000
	s_add_i32 s48, 0, 0x1c000
	v_add_u32_e32 v88, s47, v73
	v_add_u32_e32 v104, s48, v73
	ds_read_b128 v[76:79], v88
	ds_read_b128 v[80:83], v88 offset:1024
	ds_read_b128 v[84:87], v88 offset:2048
	ds_read_b128 v[88:91], v88 offset:3072
	ds_read_b128 v[92:95], v104
	ds_read_b128 v[96:99], v104 offset:1024
	ds_read_b128 v[100:103], v104 offset:2048
	ds_read_b128 v[104:107], v104 offset:3072
	s_add_u32 s0, s26, 0x40000
	s_addc_u32 s1, s27, 0
	s_mov_b32 m0, s37
	v_lshl_add_u64 v[154:155], s[0:1], 0, v[130:131]
	ds_read_b128 v[108:111], v75 offset:32768
	ds_read_b128 v[112:115], v75 offset:33792
	ds_read_b128 v[116:119], v75 offset:34816
	ds_read_b128 v[120:123], v75 offset:35840
	ds_read_b128 v[124:127], v75 offset:36864
	ds_read_b128 v[136:139], v75 offset:37888
	ds_read_b128 v[144:147], v75 offset:38912
	ds_read_b128 v[148:151], v75 offset:39936
	v_lshl_add_u64 v[154:155], s[0:1], 0, v[132:133]
	s_mov_b32 m0, s38
	s_nop 0
	s_waitcnt vmcnt(8)
	s_waitcnt lgkmcnt(0)
	s_barrier
	s_setprio 1
	s_waitcnt lgkmcnt(0)
	v_mfma_f32_16x16x32_bf16 v[62:65], v[76:79], v[108:111], v[62:65]
	v_mfma_f32_16x16x32_bf16 v[54:57], v[84:87], v[108:111], v[54:57]
	v_mfma_f32_16x16x32_bf16 v[46:49], v[76:79], v[116:119], v[46:49]
	v_mfma_f32_16x16x32_bf16 v[38:41], v[84:87], v[116:119], v[38:41]
	v_mfma_f32_16x16x32_bf16 v[30:33], v[76:79], v[124:127], v[30:33]
	v_mfma_f32_16x16x32_bf16 v[22:25], v[84:87], v[124:127], v[22:25]
	v_mfma_f32_16x16x32_bf16 v[14:17], v[76:79], v[144:147], v[14:17]
	v_mfma_f32_16x16x32_bf16 v[6:9], v[84:87], v[144:147], v[6:9]
	v_mfma_f32_16x16x32_bf16 v[62:65], v[80:83], v[112:115], v[62:65]
	v_mfma_f32_16x16x32_bf16 v[54:57], v[88:91], v[112:115], v[54:57]
	v_mfma_f32_16x16x32_bf16 v[46:49], v[80:83], v[120:123], v[46:49]
	v_mfma_f32_16x16x32_bf16 v[38:41], v[88:91], v[120:123], v[38:41]
	v_mfma_f32_16x16x32_bf16 v[30:33], v[80:83], v[136:139], v[30:33]
	v_mfma_f32_16x16x32_bf16 v[22:25], v[88:91], v[136:139], v[22:25]
	v_mfma_f32_16x16x32_bf16 v[14:17], v[80:83], v[148:151], v[14:17]
	v_mfma_f32_16x16x32_bf16 v[6:9], v[88:91], v[148:151], v[6:9]
	s_setprio 0
	s_setprio 1
	v_mfma_f32_16x16x32_bf16 v[58:61], v[92:95], v[108:111], v[58:61]
	v_mfma_f32_16x16x32_bf16 v[50:53], v[100:103], v[108:111], v[50:53]
	v_mfma_f32_16x16x32_bf16 v[42:45], v[92:95], v[116:119], v[42:45]
	v_mfma_f32_16x16x32_bf16 v[34:37], v[100:103], v[116:119], v[34:37]
	v_mfma_f32_16x16x32_bf16 v[26:29], v[92:95], v[124:127], v[26:29]
	v_mfma_f32_16x16x32_bf16 v[18:21], v[100:103], v[124:127], v[18:21]
	v_mfma_f32_16x16x32_bf16 v[10:13], v[92:95], v[144:147], v[10:13]
	v_mfma_f32_16x16x32_bf16 v[2:5], v[100:103], v[144:147], v[2:5]
	v_mfma_f32_16x16x32_bf16 v[58:61], v[96:99], v[112:115], v[58:61]
	v_mfma_f32_16x16x32_bf16 v[50:53], v[104:107], v[112:115], v[50:53]
	v_mfma_f32_16x16x32_bf16 v[42:45], v[96:99], v[120:123], v[42:45]
	v_mfma_f32_16x16x32_bf16 v[34:37], v[104:107], v[120:123], v[34:37]
	v_mfma_f32_16x16x32_bf16 v[26:29], v[96:99], v[136:139], v[26:29]
	v_mfma_f32_16x16x32_bf16 v[18:21], v[104:107], v[136:139], v[18:21]
	v_mfma_f32_16x16x32_bf16 v[10:13], v[96:99], v[148:151], v[10:13]
	v_mfma_f32_16x16x32_bf16 v[2:5], v[104:107], v[148:151], v[2:5]
	s_setprio 0
	s_barrier
	s_add_i32 s0, s47, s34
	v_lshl_add_u64 v[70:71], v[70:71], 0, s[86:87]
	s_mov_b32 m0, s0
	s_nop 0
	global_load_lds_dwordx4 v[70:71], off
	s_add_i32 m0, s0, 0x2000
	s_add_u32 s0, s24, 0x40080
	v_lshl_add_u64 v[70:71], v[128:129], 0, s[86:87]
	s_addc_u32 s1, s25, 0
	s_add_i32 s24, s48, s34
	global_load_lds_dwordx4 v[70:71], off
	v_lshl_add_u64 v[70:71], s[0:1], 0, v[0:1]
	s_mov_b32 m0, s24
	s_nop 0
	global_load_lds_dwordx4 v[70:71], off
	v_lshl_add_u64 v[70:71], s[0:1], 0, v[134:135]
	s_add_i32 m0, s24, 0x2000
	s_nop 0
	global_load_lds_dwordx4 v[70:71], off
	v_lshl_add_u64 v[70:71], v[140:141], 0, s[86:87]
	s_mov_b32 m0, s39
	s_nop 0
	global_load_lds_dwordx4 v[70:71], off
	v_lshl_add_u64 v[70:71], v[152:153], 0, s[86:87]
	s_mov_b32 m0, s40
	s_nop 0
	global_load_lds_dwordx4 v[70:71], off
	s_waitcnt vmcnt(6)
	s_waitcnt lgkmcnt(0)
	s_barrier
	s_barrier
	s_add_i32 s46, s46, 2
	s_add_u32 s22, s22, 0x100
	s_addc_u32 s23, s23, 0
	s_add_u32 s44, s44, 0x100
	s_addc_u32 s45, s45, 0
	s_cmp_gt_u32 s46, 13
	s_cbranch_scc0 .LBB0_419
	s_and_b64 vcc, exec, s[10:11]
	s_cbranch_vccz .LBB0_422
	s_barrier
